# PC: latent pass-1 SSM scan jobs moved to the 64 workgroups that have no FFT1 GEMM tile (14 jobs per workgroup)
# baseline (speedup 1.0000x reference)
_Z8mega_fwd4Args:
	s_mov_b32 s100, 0
	s_load_dwordx4 s[24:27], s[0:1], 0x120
	s_add_u32 s4, s0, 0x128
	v_and_b32_e32 v224, 0x3ff, v0
	s_mov_b32 s43, s2
	s_addc_u32 s5, s1, 0
	v_cmp_gt_u32_e32 vcc, 4, v224
	s_and_saveexec_b64 s[2:3], vcc
	v_lshl_add_u32 v1, v224, 2, 0
	v_add_u32_e32 v1, 0x20000, v1
	v_mov_b32_e32 v2, 0
	ds_write_b32 v1, v2
	s_or_b64 exec, exec, s[2:3]
	s_load_dwordx8 s[8:15], s[0:1], 0x100
	s_waitcnt lgkmcnt(0)
	s_cmp_gt_i32 s24, -1
	s_barrier
	v_writelane_b32 v249, s8, 0
	s_nop 1
	v_writelane_b32 v249, s9, 1
	v_writelane_b32 v249, s10, 2
	v_writelane_b32 v249, s11, 3
	v_writelane_b32 v249, s12, 4
	v_writelane_b32 v249, s13, 5
	v_writelane_b32 v249, s14, 6
	v_writelane_b32 v249, s15, 7
	s_cbranch_scc1 .LBB0_14
	v_lshrrev_b32_e32 v1, 20, v0
	v_lshrrev_b32_e32 v0, 10, v0
	v_or_b32_e32 v0, v0, v1
	s_movk_i32 s2, 0x3ff
	v_and_or_b32 v0, v0, s2, v224
	v_cmp_eq_u32_e32 vcc, 0, v0
	s_barrier
	s_and_saveexec_b64 s[2:3], vcc
	s_cbranch_execz .LBB0_13
	buffer_wbl2 sc1
	s_load_dwordx2 s[4:5], s[4:5], 0x58
	s_mov_b64 s[6:7], exec
	v_mbcnt_lo_u32_b32 v0, s6, 0
	v_mbcnt_hi_u32_b32 v0, s7, v0
	v_cmp_eq_u32_e32 vcc, 0, v0
	s_waitcnt lgkmcnt(0)
	s_load_dword s10, s[4:5], 0x28
	s_and_saveexec_b64 s[8:9], vcc
	s_cbranch_execz .LBB0_6
	s_bcnt1_i32_b64 s6, s[6:7]
	v_mov_b32_e32 v1, 0
	v_mov_b32_e32 v2, s6
	global_atomic_add v1, v1, v2, s[4:5] offset:32 sc0

.LBB0_624:
	v_lshl_add_u64 v[2:3], v[2:3], 3, s[2:3]
	s_nop 0
	global_store_dwordx2 v[2:3], v[106:107], off
	s_cmpk_lg_u32 s26, 0x100
	s_cbranch_scc1 .Lssa_orig
	s_cmpk_gt_i32 s39, 0x7ff
	s_cbranch_scc0 .Lssa_after_ctx
	s_cmp_eq_u32 s100, 0
	s_cbranch_scc1 .LBB0_633
	s_mov_b32 s39, s100
	s_mov_b32 s100, 0
	s_branch .LBB0_625
.Lssa_after_ctx:
	s_cmpk_lt_u32 s43, 0xc0
	s_cbranch_scc1 .LBB0_633
	s_sub_i32 s39, s43, 0xc0
	s_mul_i32 s39, s39, 14
	s_add_i32 s39, s39, s27
	s_addk_i32 s39, 0x800
	s_mov_b32 s100, 0
	s_cmp_gt_u32 s27, 5
	s_cbranch_scc1 .LBB0_625
	s_add_i32 s100, s39, 8
	s_branch .LBB0_625
